# transpose phase: both tile loads of a unit issued together before the LDS writes (2 sites), on top of RoPE/QK/conversion/hyena fixes
# speedup vs baseline: 1.0055x; 1.0055x over previous
.LBB0_1703:
	global_load_dwordx4 v[18:21], v[10:11], off
	v_lshl_add_u64 v[10:11], v[10:11], 0, s[8:9]
	global_load_dwordx4 v[24:27], v[10:11], off
	s_waitcnt vmcnt(1)
	ds_write2_b32 v2, v18, v19 offset1:1
	ds_write2_b32 v2, v20, v21 offset0:2 offset1:3
	v_add_u32_e32 v2, 0x1080, v2
	s_waitcnt vmcnt(0)
	ds_write2_b32 v2, v24, v25 offset1:1
	ds_write2_b32 v2, v26, v27 offset0:2 offset1:3
